# RWKV staging fold: LDS writes spread between the fold FMAs instead of one burst
# baseline (speedup 1.0000x reference)
.LBB0_659:
	s_or_b64 exec, exec, s[10:11]
	s_or_b32 s22, s4, 32
	s_mov_b32 s23, s5
	v_lshl_add_u64 v[6:7], s[22:23], 0, v[26:27]
	v_lshlrev_b64 v[6:7], 11, v[6:7]
	v_lshlrev_b32_e32 v25, 1, v55
	v_or_b32_e32 v6, v6, v25
	v_lshl_add_u64 v[8:9], s[70:71], 0, v[6:7]
	v_lshl_add_u64 v[10:11], s[12:13], 0, v[6:7]
	v_lshl_add_u64 v[12:13], s[14:15], 0, v[6:7]
	v_lshl_add_u64 v[14:15], s[16:17], 0, v[6:7]
	v_lshl_add_u64 v[16:17], s[18:19], 0, v[6:7]
	v_or_b32_e32 v6, 0x800, v6
	global_load_dwordx2 v[10:11], v[10:11], off
	v_lshl_add_u64 v[18:19], s[12:13], 0, v[6:7]
	global_load_dwordx2 v[14:15], v[14:15], off
	s_nop 0
	global_load_dwordx2 v[18:19], v[18:19], off
	s_nop 0
	global_load_dwordx2 v[20:21], v[8:9], off
	global_load_dwordx2 v[56:57], v[12:13], off
	s_nop 0
	global_load_dwordx2 v[12:13], v[8:9], off offset:2048
	v_lshl_add_u64 v[8:9], s[16:17], 0, v[6:7]
	global_load_dwordx2 v[64:65], v[8:9], off
	global_load_dwordx2 v[68:69], v[16:17], off
	v_cvt_f32_f16_sdwa v9, v3 dst_sel:DWORD dst_unused:UNUSED_PAD src0_sel:WORD_1
	v_cvt_f32_f16_e32 v8, v3
	s_or_b32 s26, s4, 64
	s_mov_b32 s27, s5
	v_lshl_add_u64 v[34:35], s[22:23], 0, v[4:5]
	v_lshl_add_u64 v[36:37], s[26:27], 0, v[26:27]
	v_lshlrev_b32_e32 v1, 6, v4
	s_mov_b32 s11, 0
	v_lshlrev_b32_e32 v24, 2, v58
	v_lshl_add_u64 v[38:39], s[26:27], 0, v[4:5]
	v_lshlrev_b64 v[34:35], 11, v[34:35]
	v_lshlrev_b64 v[36:37], 11, v[36:37]
	v_add3_u32 v1, 0, v1, v24
	s_mov_b32 s7, s11
	v_lshlrev_b64 v[38:39], 11, v[38:39]
	v_lshl_add_u64 v[34:35], s[20:21], 0, v[34:35]
	v_or_b32_e32 v36, v36, v25
	v_lshl_add_u64 v[38:39], s[20:21], 0, v[38:39]
	ds_write_b64 v1, v[8:9] offset:37632
	ds_read_b128 v[198:201], v216 offset:36864
	ds_read_b128 v[202:205], v216 offset:36880
	ds_read2_b32 v[206:207], v220 offset1:16
	s_waitcnt lgkmcnt(0)
	v_mul_f32_e32 v210, 0x41800000, v200
	v_mul_f32_e32 v211, 0x41800000, v202
	v_mul_f32_e32 v212, 0x41800000, v204
	v_fma_f32 v213, -v204, v199, v203
	v_fma_f32 v121, -v198, v120, v121
	v_fma_f32 v123, -v198, v122, v123
	ds_write_b128 v218, v[120:123]
	v_fma_f32 v124, -v210, v120, v124
	v_fma_f32 v125, -v211, v120, v125
	v_fma_f32 v125, -v212, v121, v125
	v_fma_f32 v126, -v210, v122, v126
	v_fma_f32 v127, -v211, v122, v127
	v_fma_f32 v127, -v212, v123, v127
	ds_write_b128 v218, v[124:127] offset:256
	v_fma_f32 v129, -v198, v128, v129
	v_fma_f32 v131, -v198, v130, v131
	ds_write_b128 v218, v[128:131] offset:512
	v_fma_f32 v132, -v210, v128, v132
	v_fma_f32 v133, -v211, v128, v133
	v_fma_f32 v133, -v212, v129, v133
	v_fma_f32 v134, -v210, v130, v134
	v_fma_f32 v135, -v211, v130, v135
	v_fma_f32 v135, -v212, v131, v135
	ds_write_b128 v218, v[132:135] offset:768
	v_fma_f32 v182, -v199, v186, v182
	v_fma_f32 v183, -v199, v187, v183
	v_fma_f32 v184, -v199, v188, v184
	v_fma_f32 v185, -v199, v189, v185
	ds_write_b128 v218, v[182:185] offset:1280
	v_mul_f32_e32 v208, v206, v201
	v_mul_f32_e32 v209, v206, v213
	v_fmac_f32_e32 v209, v207, v205
	ds_write_b128 v222, v[206:209]
	v_lshl_add_u64 v[8:9], v[34:35], 0, s[6:7]
	v_lshl_add_u64 v[34:35], s[14:15], 0, v[36:37]
	v_lshl_add_u64 v[40:41], s[16:17], 0, v[36:37]
	v_lshl_add_u64 v[50:51], s[14:15], 0, v[6:7]
	v_lshl_add_u64 v[46:47], s[18:19], 0, v[36:37]
	v_lshl_add_u64 v[48:49], v[38:39], 0, s[6:7]
	v_lshl_add_u64 v[6:7], s[18:19], 0, v[6:7]
	global_load_dwordx2 v[38:39], v[34:35], off
	global_load_dwordx2 v[42:43], v[40:41], off
	s_nop 0
	global_load_dwordx2 v[40:41], v[46:47], off
	global_load_dwordx2 v[70:71], v[50:51], off
	global_load_dwordx2 v[72:73], v[6:7], off
	s_add_i32 s10, 0, 0x11b00
	s_mov_b32 s9, s11
	v_lshl_add_u64 v[16:17], s[70:71], 0, v[36:37]
	v_lshl_add_u64 v[44:45], s[12:13], 0, v[36:37]
	v_or_b32_e32 v36, 0x800, v36
	v_mov_b32_e32 v3, 0
	v_lshl_add_u32 v22, v22, 2, s10
	v_lshl_add_u64 v[8:9], v[8:9], 0, s[8:9]
	v_lshl_add_u64 v[34:35], s[12:13], 0, v[36:37]
	v_lshl_add_u64 v[46:47], s[14:15], 0, v[36:37]
	v_lshl_add_u64 v[66:67], s[16:17], 0, v[36:37]
	v_lshl_add_u64 v[36:37], s[18:19], 0, v[36:37]
	v_lshl_add_u64 v[48:49], v[48:49], 0, s[8:9]
	v_add_u32_e32 v76, v22, v62
	v_lshl_add_u64 v[6:7], v[8:9], 0, v[2:3]
	global_load_dwordx2 v[52:53], v[34:35], off
	s_nop 0
	global_load_dwordx2 v[34:35], v[46:47], off
	s_nop 0
	global_load_dwordx2 v[46:47], v[66:67], off
	s_nop 0
	global_load_dwordx2 v[36:37], v[36:37], off
	v_lshl_add_u64 v[8:9], v[48:49], 0, v[2:3]
	global_load_dwordx2 v[50:51], v[44:45], off
	global_load_dword v22, v[6:7], off
	global_load_dwordx2 v[48:49], v[16:17], off
	s_nop 0
	global_load_dwordx2 v[44:45], v[16:17], off offset:2048
	global_load_dword v61, v[8:9], off
	s_waitcnt lgkmcnt(0)
	s_mov_b32 s61, 1
	s_waitcnt lgkmcnt(0)
	v_mov_b32_e32 v226, s61
	s_mov_b64 s[58:59], exec
	s_mov_b64 exec, 1
	ds_write_b32 v224, v226
	s_mov_b64 exec, s[58:59]
	s_waitcnt lgkmcnt(0)
	s_barrier
	v_lshlrev_b32_e32 v60, 4, v4
	v_add_u32_e32 v77, 0, v23
	s_waitcnt vmcnt(19)
	v_cvt_f32_f16_e32 v16, v18
	v_cvt_f32_f16_sdwa v17, v18 dst_sel:DWORD dst_unused:UNUSED_PAD src0_sel:WORD_1
	v_cvt_f32_f16_e32 v8, v10
	v_cvt_f32_f16_sdwa v9, v10 dst_sel:DWORD dst_unused:UNUSED_PAD src0_sel:WORD_1
	v_cvt_f32_f16_e32 v10, v11
	v_pk_add_f32 v[78:79], v[16:17], 1.0 op_sel_hi:[1,0] neg_lo:[1,0] neg_hi:[1,0]
	v_cvt_f32_f16_e32 v16, v19
	v_cvt_f32_f16_sdwa v17, v19 dst_sel:DWORD dst_unused:UNUSED_PAD src0_sel:WORD_1
	v_cvt_f32_f16_sdwa v11, v11 dst_sel:DWORD dst_unused:UNUSED_PAD src0_sel:WORD_1
	s_waitcnt vmcnt(16)
	v_cvt_f32_f16_e32 v80, v12
	v_cvt_f32_f16_sdwa v81, v12 dst_sel:DWORD dst_unused:UNUSED_PAD src0_sel:WORD_1
	s_waitcnt vmcnt(15)
	v_cvt_f32_f16_e32 v82, v64
	v_cvt_f32_f16_sdwa v83, v64 dst_sel:DWORD dst_unused:UNUSED_PAD src0_sel:WORD_1
	v_cvt_f32_f16_e32 v92, v65
	v_cvt_f32_f16_sdwa v93, v65 dst_sel:DWORD dst_unused:UNUSED_PAD src0_sel:WORD_1
	v_cvt_f32_f16_e32 v94, v13
	v_cvt_f32_f16_sdwa v95, v13 dst_sel:DWORD dst_unused:UNUSED_PAD src0_sel:WORD_1
	v_cvt_f32_f16_e32 v6, v14
	v_cvt_f32_f16_sdwa v7, v14 dst_sel:DWORD dst_unused:UNUSED_PAD src0_sel:WORD_1
	v_cvt_f32_f16_e32 v74, v20
	v_pk_add_f32 v[66:67], v[8:9], 1.0 op_sel_hi:[1,0] neg_lo:[1,0] neg_hi:[1,0]
	v_cvt_f32_f16_sdwa v75, v20 dst_sel:DWORD dst_unused:UNUSED_PAD src0_sel:WORD_1
	v_cvt_f32_f16_e32 v8, v15
	v_cvt_f32_f16_sdwa v9, v15 dst_sel:DWORD dst_unused:UNUSED_PAD src0_sel:WORD_1
	v_cvt_f32_f16_e32 v90, v21
	v_cvt_f32_f16_sdwa v91, v21 dst_sel:DWORD dst_unused:UNUSED_PAD src0_sel:WORD_1
	v_pk_add_f32 v[86:87], v[16:17], 1.0 op_sel_hi:[1,0] neg_lo:[1,0] neg_hi:[1,0]
	v_pk_add_f32 v[88:89], v[10:11], 1.0 op_sel_hi:[1,0] neg_lo:[1,0] neg_hi:[1,0]
	v_pk_mul_f32 v[84:85], v[78:79], v[80:81]
	v_pk_mul_f32 v[14:15], v[66:67], v[82:83]
	v_pk_mul_f32 v[16:17], v[88:89], v[92:93]
	v_pk_mul_f32 v[96:97], v[86:87], v[94:95]
	v_pk_mul_f32 v[10:11], v[66:67], v[74:75]
	v_pk_mul_f32 v[12:13], v[88:89], v[90:91]
	v_pk_mul_f32 v[18:19], v[66:67], v[84:85]
	v_pk_mul_f32 v[20:21], v[88:89], v[96:97]
	v_pk_mul_f32 v[64:65], v[66:67], v[78:79]
	v_pk_mul_f32 v[66:67], v[88:89], v[86:87]
	v_mov_b32_e32 v120, v6
	v_mov_b32_e32 v121, v14
	v_mov_b32_e32 v122, v7
	v_mov_b32_e32 v123, v15
	v_mov_b32_e32 v124, v10
	v_mov_b32_e32 v125, v18
	v_mov_b32_e32 v126, v11
	v_mov_b32_e32 v127, v19
	v_mov_b32_e32 v128, v8
	v_mov_b32_e32 v129, v16
	v_mov_b32_e32 v130, v9
	v_mov_b32_e32 v131, v17
	v_mov_b32_e32 v132, v12
	v_mov_b32_e32 v133, v20
	v_mov_b32_e32 v134, v13
	v_mov_b32_e32 v135, v21
	ds_write_b128 v76, v[64:67] offset:1024
	s_waitcnt vmcnt(14)
	v_cvt_f32_f16_e32 v14, v68
	v_cvt_f32_f16_sdwa v16, v68 dst_sel:DWORD dst_unused:UNUSED_PAD src0_sel:WORD_1
	v_cvt_f32_f16_e32 v15, v56
	v_cvt_f32_f16_sdwa v17, v56 dst_sel:DWORD dst_unused:UNUSED_PAD src0_sel:WORD_1
	v_cvt_f32_f16_e32 v21, v57
	v_cvt_f32_f16_sdwa v57, v57 dst_sel:DWORD dst_unused:UNUSED_PAD src0_sel:WORD_1
	v_cvt_f32_f16_e32 v20, v69
	v_cvt_f32_f16_sdwa v56, v69 dst_sel:DWORD dst_unused:UNUSED_PAD src0_sel:WORD_1
	v_mov_b32_e32 v8, v14
	v_mov_b32_e32 v9, v16
	v_mov_b32_e32 v6, v15
	v_mov_b32_e32 v7, v17
	v_pk_mul_f32 v[10:11], v[78:79], v[8:9]
	v_mov_b32_e32 v8, v21
	v_mov_b32_e32 v9, v57
	v_pk_mul_f32 v[6:7], v[78:79], v[6:7]
	v_pk_mul_f32 v[8:9], v[86:87], v[8:9]
	v_mov_b32_e32 v12, v20
	v_mov_b32_e32 v13, v56
	v_mov_b32_e32 v18, v83
	v_pk_mul_f32 v[12:13], v[86:87], v[12:13]
	v_mov_b32_e32 v182, v6
	v_mov_b32_e32 v183, v7
	v_mov_b32_e32 v184, v8
	v_mov_b32_e32 v185, v9
	ds_write_b128 v76, v[10:13] offset:1536
	v_pk_fma_f32 v[6:7], v[82:83], v[14:15], 0 op_sel_hi:[0,1,0]
	v_pk_fma_f32 v[6:7], v[18:19], v[16:17], v[6:7] op_sel_hi:[0,1,1]
	v_mov_b32_e32 v10, v75
	v_pk_fma_f32 v[18:19], v[74:75], v[14:15], 0 op_sel_hi:[0,1,0]
	v_pk_fma_f32 v[14:15], v[84:85], v[14:15], 0 op_sel_hi:[0,1,0]
	v_pk_fma_f32 v[10:11], v[10:11], v[16:17], v[18:19] op_sel_hi:[0,1,1]
	v_pk_fma_f32 v[14:15], v[84:85], v[16:17], v[14:15] op_sel:[1,0,0]
	v_mov_b32_e32 v54, v93
	v_pk_fma_f32 v[6:7], v[92:93], v[20:21], v[6:7] op_sel_hi:[0,1,1]
	v_mov_b32_e32 v12, v91
	v_pk_fma_f32 v[10:11], v[90:91], v[20:21], v[10:11] op_sel_hi:[0,1,1]
	v_pk_fma_f32 v[14:15], v[96:97], v[20:21], v[14:15] op_sel_hi:[0,1,1]
	v_pk_fma_f32 v[6:7], v[54:55], v[56:57], v[6:7] op_sel_hi:[0,1,1]
	v_pk_fma_f32 v[10:11], v[12:13], v[56:57], v[10:11] op_sel_hi:[0,1,1]
	v_pk_fma_f32 v[14:15], v[96:97], v[56:57], v[14:15] op_sel:[1,0,0]
	s_waitcnt vmcnt(10)
	v_cvt_f32_f16_e32 v57, v70
	v_cvt_f32_f16_sdwa v65, v70 dst_sel:DWORD dst_unused:UNUSED_PAD src0_sel:WORD_1
	v_cvt_f32_f16_e32 v67, v71
	v_cvt_f32_f16_sdwa v69, v71 dst_sel:DWORD dst_unused:UNUSED_PAD src0_sel:WORD_1
	s_waitcnt vmcnt(9)
	v_cvt_f32_f16_e32 v56, v72
	v_cvt_f32_f16_sdwa v64, v72 dst_sel:DWORD dst_unused:UNUSED_PAD src0_sel:WORD_1
	v_cvt_f32_f16_e32 v66, v73
	v_cvt_f32_f16_sdwa v68, v73 dst_sel:DWORD dst_unused:UNUSED_PAD src0_sel:WORD_1
	v_mov_b32_e32 v18, v57
	v_mov_b32_e32 v19, v65
	v_mov_b32_e32 v20, v67
	v_mov_b32_e32 v21, v69
	ds_write_b128 v76, v[18:21] offset:1792
	v_mov_b32_e32 v18, v56
	v_mov_b32_e32 v19, v64
	v_mov_b32_e32 v20, v66
	v_mov_b32_e32 v21, v68
	v_mov_b32_e32 v54, v81
	ds_write_b128 v76, v[18:21] offset:2048
	v_mov_b32_e32 v186, v18
	v_mov_b32_e32 v187, v19
	v_mov_b32_e32 v188, v20
	v_mov_b32_e32 v189, v21
	v_pk_fma_f32 v[18:19], v[80:81], v[56:57], 0 op_sel_hi:[0,1,0]
	v_pk_fma_f32 v[18:19], v[54:55], v[64:65], v[18:19] op_sel_hi:[0,1,1]
	v_mov_b32_e32 v70, v95
	v_pk_fma_f32 v[18:19], v[94:95], v[66:67], v[18:19] op_sel_hi:[0,1,1]
	v_pk_fma_f32 v[18:19], v[70:71], v[68:69], v[18:19] op_sel_hi:[0,1,1]
	v_mov_b32_dpp v8, v6 row_ror:8 row_mask:0xf bank_mask:0xf bound_ctrl:1
	v_mov_b32_dpp v9, v7 row_ror:8 row_mask:0xf bank_mask:0xf bound_ctrl:1
	v_mov_b32_dpp v12, v10 row_ror:8 row_mask:0xf bank_mask:0xf bound_ctrl:1
	v_mov_b32_dpp v13, v11 row_ror:8 row_mask:0xf bank_mask:0xf bound_ctrl:1
	v_mov_b32_dpp v16, v14 row_ror:8 row_mask:0xf bank_mask:0xf bound_ctrl:1
	v_mov_b32_dpp v17, v15 row_ror:8 row_mask:0xf bank_mask:0xf bound_ctrl:1
	v_mov_b32_dpp v20, v18 row_ror:8 row_mask:0xf bank_mask:0xf bound_ctrl:1
	v_mov_b32_dpp v21, v19 row_ror:8 row_mask:0xf bank_mask:0xf bound_ctrl:1
	v_pk_add_f32 v[6:7], v[6:7], v[8:9]
	v_pk_add_f32 v[10:11], v[10:11], v[12:13]
	v_pk_add_f32 v[14:15], v[14:15], v[16:17]
	v_pk_add_f32 v[18:19], v[18:19], v[20:21]
	v_mov_b32_dpp v8, v6 row_ror:4 row_mask:0xf bank_mask:0xf bound_ctrl:1
	v_mov_b32_dpp v9, v7 row_ror:4 row_mask:0xf bank_mask:0xf bound_ctrl:1
	v_mov_b32_dpp v12, v10 row_ror:4 row_mask:0xf bank_mask:0xf bound_ctrl:1
	v_mov_b32_dpp v13, v11 row_ror:4 row_mask:0xf bank_mask:0xf bound_ctrl:1
	v_mov_b32_dpp v16, v14 row_ror:4 row_mask:0xf bank_mask:0xf bound_ctrl:1
	v_mov_b32_dpp v17, v15 row_ror:4 row_mask:0xf bank_mask:0xf bound_ctrl:1
	v_mov_b32_dpp v20, v18 row_ror:4 row_mask:0xf bank_mask:0xf bound_ctrl:1
	v_mov_b32_dpp v21, v19 row_ror:4 row_mask:0xf bank_mask:0xf bound_ctrl:1
	v_pk_add_f32 v[6:7], v[6:7], v[8:9]
	v_pk_add_f32 v[10:11], v[10:11], v[12:13]
	v_pk_add_f32 v[14:15], v[14:15], v[16:17]
	v_pk_add_f32 v[18:19], v[18:19], v[20:21]
	v_mov_b32_dpp v8, v6 row_ror:2 row_mask:0xf bank_mask:0xf bound_ctrl:1
	v_mov_b32_dpp v9, v7 row_ror:2 row_mask:0xf bank_mask:0xf bound_ctrl:1
	v_mov_b32_dpp v12, v10 row_ror:2 row_mask:0xf bank_mask:0xf bound_ctrl:1
	v_mov_b32_dpp v13, v11 row_ror:2 row_mask:0xf bank_mask:0xf bound_ctrl:1
	v_mov_b32_dpp v16, v14 row_ror:2 row_mask:0xf bank_mask:0xf bound_ctrl:1
	v_mov_b32_dpp v17, v15 row_ror:2 row_mask:0xf bank_mask:0xf bound_ctrl:1
	v_mov_b32_dpp v20, v18 row_ror:2 row_mask:0xf bank_mask:0xf bound_ctrl:1
	v_mov_b32_dpp v21, v19 row_ror:2 row_mask:0xf bank_mask:0xf bound_ctrl:1
	v_pk_add_f32 v[6:7], v[6:7], v[8:9]
	v_pk_add_f32 v[10:11], v[10:11], v[12:13]
	v_pk_add_f32 v[14:15], v[14:15], v[16:17]
	v_pk_add_f32 v[18:19], v[18:19], v[20:21]
	v_mov_b32_dpp v8, v6 row_ror:1 row_mask:0xf bank_mask:0xf bound_ctrl:1
	v_mov_b32_dpp v9, v7 row_ror:1 row_mask:0xf bank_mask:0xf bound_ctrl:1
	v_mov_b32_dpp v12, v10 row_ror:1 row_mask:0xf bank_mask:0xf bound_ctrl:1
	v_mov_b32_dpp v13, v11 row_ror:1 row_mask:0xf bank_mask:0xf bound_ctrl:1
	v_mov_b32_dpp v16, v14 row_ror:1 row_mask:0xf bank_mask:0xf bound_ctrl:1
	v_mov_b32_dpp v17, v15 row_ror:1 row_mask:0xf bank_mask:0xf bound_ctrl:1
	v_mov_b32_dpp v20, v18 row_ror:1 row_mask:0xf bank_mask:0xf bound_ctrl:1
	v_mov_b32_dpp v21, v19 row_ror:1 row_mask:0xf bank_mask:0xf bound_ctrl:1
	s_and_saveexec_b64 s[22:23], s[0:1]
	s_cbranch_execz .LBB0_661
	v_pk_add_f32 v[6:7], v[6:7], v[8:9]
	v_pk_add_f32 v[8:9], v[10:11], v[12:13]
	s_mov_b32 s10, 0x3d800000
	v_pk_mul_f32 v[8:9], v[8:9], s[10:11] op_sel_hi:[1,0]
	v_add_u32_e32 v10, 0x1ab00, v77
	ds_write_b128 v10, v[6:9]
	v_pk_add_f32 v[6:7], v[14:15], v[16:17]
	v_pk_add_f32 v[8:9], v[18:19], v[20:21]
	v_pk_mul_f32 v[6:7], v[6:7], s[10:11] op_sel_hi:[1,0]
	v_pk_mul_f32 v[8:9], v[8:9], s[10:11] op_sel_hi:[1,0]
	ds_write_b128 v10, v[6:9] offset:16
.LBB0_661:
	s_or_b64 exec, exec, s[22:23]
	v_lshlrev_b32_e32 v6, 2, v60
	s_add_i32 s7, 0, 0x1ae00
	v_add3_u32 v78, s7, v6, v24
	s_add_u32 s7, s20, s6
	s_addc_u32 s9, s21, 0
	s_add_u32 s20, s7, s8
	s_waitcnt vmcnt(3)
	v_cvt_f32_f16_sdwa v7, v22 dst_sel:DWORD dst_unused:UNUSED_PAD src0_sel:WORD_1
	v_cvt_f32_f16_e32 v6, v22
	s_addc_u32 s21, s9, 0
	v_lshl_add_u64 v[56:57], s[20:21], 0, v[2:3]
	s_mov_b64 s[20:21], 0x18000
	v_or_b32_e32 v54, 0x400, v55
	v_lshl_add_u64 v[16:17], v[28:29], 0, s[20:21]
	ds_write_b64 v78, v[6:7]
	ds_read_b128 v[198:201], v217 offset:36864
	ds_read_b128 v[202:205], v217 offset:36880
	ds_read2_b32 v[206:207], v221 offset1:16
	s_waitcnt lgkmcnt(0)
	v_mul_f32_e32 v210, 0x41800000, v200
	v_mul_f32_e32 v211, 0x41800000, v202
	v_mul_f32_e32 v212, 0x41800000, v204
	v_fma_f32 v213, -v204, v199, v203
	v_fma_f32 v121, -v198, v120, v121
	v_fma_f32 v123, -v198, v122, v123
	ds_write_b128 v219, v[120:123]
	v_fma_f32 v124, -v210, v120, v124
	v_fma_f32 v125, -v211, v120, v125
	v_fma_f32 v125, -v212, v121, v125
	v_fma_f32 v126, -v210, v122, v126
	v_fma_f32 v127, -v211, v122, v127
	v_fma_f32 v127, -v212, v123, v127
	ds_write_b128 v219, v[124:127] offset:256
	v_fma_f32 v129, -v198, v128, v129
	v_fma_f32 v131, -v198, v130, v131
	ds_write_b128 v219, v[128:131] offset:512
	v_fma_f32 v132, -v210, v128, v132
	v_fma_f32 v133, -v211, v128, v133
	v_fma_f32 v133, -v212, v129, v133
	v_fma_f32 v134, -v210, v130, v134
	v_fma_f32 v135, -v211, v130, v135
	v_fma_f32 v135, -v212, v131, v135
	ds_write_b128 v219, v[132:135] offset:768
	v_fma_f32 v182, -v199, v186, v182
	v_fma_f32 v183, -v199, v187, v183
	v_fma_f32 v184, -v199, v188, v184
	v_fma_f32 v185, -v199, v189, v185
	ds_write_b128 v219, v[182:185] offset:1280
	v_mul_f32_e32 v208, v206, v201
	v_mul_f32_e32 v209, v206, v213
	v_fmac_f32_e32 v209, v207, v205
	ds_write_b128 v223, v[206:209]
	v_or_b32_e32 v6, v16, v55
	v_mov_b32_e32 v7, v17
	v_or_b32_e32 v16, v16, v54
	v_lshlrev_b64 v[12:13], 1, v[6:7]
	v_lshlrev_b64 v[22:23], 1, v[16:17]
	v_lshl_add_u64 v[56:57], v[56:57], 0, v[32:33]
	s_mov_b32 s7, 0x30000
	v_lshl_add_u64 v[6:7], s[70:71], 0, v[12:13]
	v_lshl_add_u64 v[8:9], s[12:13], 0, v[12:13]
	v_lshl_add_u64 v[10:11], s[14:15], 0, v[12:13]
	v_lshl_add_u64 v[14:15], s[16:17], 0, v[12:13]
	v_lshl_add_u64 v[18:19], s[18:19], 0, v[12:13]
	v_lshl_add_u64 v[16:17], s[70:71], 0, v[22:23]
	v_lshl_add_u64 v[20:21], s[12:13], 0, v[22:23]
	v_lshl_add_u64 v[24:25], s[14:15], 0, v[22:23]
	v_add_co_u32_e32 v32, vcc, s7, v56
	global_load_dwordx2 v[6:7], v[6:7], off
	s_nop 0
	global_load_dwordx2 v[8:9], v[8:9], off
	s_nop 0
	global_load_dwordx2 v[10:11], v[10:11], off
	s_nop 0
	global_load_dwordx2 v[12:13], v[14:15], off
	s_nop 0
	global_load_dwordx2 v[14:15], v[18:19], off
	s_nop 0
	global_load_dwordx2 v[18:19], v[16:17], off
	s_nop 0
	global_load_dwordx2 v[16:17], v[20:21], off
	s_nop 0
	global_load_dwordx2 v[20:21], v[24:25], off
	v_lshl_add_u64 v[24:25], s[16:17], 0, v[22:23]
	v_lshl_add_u64 v[22:23], s[18:19], 0, v[22:23]
	v_addc_co_u32_e32 v33, vcc, 0, v57, vcc
	global_load_dwordx2 v[24:25], v[24:25], off
	s_nop 0
	global_load_dwordx2 v[22:23], v[22:23], off
	v_cvt_f32_f16_sdwa v67, v50 dst_sel:DWORD dst_unused:UNUSED_PAD src0_sel:WORD_1
	global_load_dword v79, v[32:33], off
	v_cvt_f32_f16_e32 v66, v50
	v_cvt_f32_f16_sdwa v33, v52 dst_sel:DWORD dst_unused:UNUSED_PAD src0_sel:WORD_1
	v_cvt_f32_f16_e32 v32, v52
	v_cvt_f32_f16_sdwa v71, v53 dst_sel:DWORD dst_unused:UNUSED_PAD src0_sel:WORD_1
	v_cvt_f32_f16_e32 v70, v53
	s_waitcnt vmcnt(12)
	v_cvt_f32_f16_sdwa v75, v44 dst_sel:DWORD dst_unused:UNUSED_PAD src0_sel:WORD_1
	v_cvt_f32_f16_e32 v74, v44
	v_cvt_f32_f16_sdwa v53, v51 dst_sel:DWORD dst_unused:UNUSED_PAD src0_sel:WORD_1
	v_cvt_f32_f16_e32 v52, v51
	v_cvt_f32_f16_sdwa v93, v45 dst_sel:DWORD dst_unused:UNUSED_PAD src0_sel:WORD_1
	v_cvt_f32_f16_e32 v92, v45
	v_cvt_f32_f16_sdwa v65, v42 dst_sel:DWORD dst_unused:UNUSED_PAD src0_sel:WORD_1
	v_cvt_f32_f16_e32 v64, v42
	v_pk_add_f32 v[68:69], v[66:67], 1.0 op_sel_hi:[1,0] neg_lo:[1,0] neg_hi:[1,0]
	v_cvt_f32_f16_sdwa v73, v48 dst_sel:DWORD dst_unused:UNUSED_PAD src0_sel:WORD_1
	v_cvt_f32_f16_e32 v72, v48
	v_cvt_f32_f16_sdwa v83, v46 dst_sel:DWORD dst_unused:UNUSED_PAD src0_sel:WORD_1
	v_cvt_f32_f16_e32 v82, v46
	v_cvt_f32_f16_sdwa v67, v43 dst_sel:DWORD dst_unused:UNUSED_PAD src0_sel:WORD_1
	v_cvt_f32_f16_e32 v66, v43
	v_cvt_f32_f16_sdwa v89, v49 dst_sel:DWORD dst_unused:UNUSED_PAD src0_sel:WORD_1
	v_cvt_f32_f16_e32 v88, v49
	v_cvt_f32_f16_sdwa v91, v47 dst_sel:DWORD dst_unused:UNUSED_PAD src0_sel:WORD_1
	v_cvt_f32_f16_e32 v90, v47
	v_pk_add_f32 v[32:33], v[32:33], 1.0 op_sel_hi:[1,0] neg_lo:[1,0] neg_hi:[1,0]
	v_pk_add_f32 v[86:87], v[70:71], 1.0 op_sel_hi:[1,0] neg_lo:[1,0] neg_hi:[1,0]
	v_pk_mul_f32 v[84:85], v[32:33], v[74:75]
	v_pk_add_f32 v[70:71], v[52:53], 1.0 op_sel_hi:[1,0] neg_lo:[1,0] neg_hi:[1,0]
	v_pk_mul_f32 v[94:95], v[86:87], v[92:93]
	v_pk_mul_f32 v[50:51], v[68:69], v[84:85]
	v_pk_mul_f32 v[52:53], v[70:71], v[94:95]
	v_add_u32_e32 v80, v59, v62
	s_waitcnt lgkmcnt(0)
	s_cselect_b32 s62, 1, 0
	s_add_i32 s61, s61, 1
	s_waitcnt lgkmcnt(0)
	v_mov_b32_e32 v226, s61
	s_mov_b64 s[58:59], exec
	s_mov_b64 exec, 1
	ds_write_b32 v224, v226
	s_mov_b64 exec, s[58:59]
	s_sub_i32 s63, s61, 1

.LBB0_663:
	s_or_b64 exec, exec, s[20:21]
	s_add_u32 s20, s78, 0xf000000
	s_addc_u32 s21, s79, 0
	s_add_u32 s7, s20, s6
	s_addc_u32 s9, s21, 0
	s_add_u32 s22, s7, s8
	s_addc_u32 s23, s9, 0
	v_mov_b32_e32 v3, 0
	s_waitcnt vmcnt(11)
	v_cvt_f32_f16_sdwa v35, v61 dst_sel:DWORD dst_unused:UNUSED_PAD src0_sel:WORD_1
	v_cvt_f32_f16_e32 v34, v61
	v_lshl_add_u64 v[32:33], s[22:23], 0, v[2:3]
	s_mov_b64 s[22:23], 0x20000
	v_lshl_add_u64 v[38:39], v[28:29], 0, s[22:23]
	v_or_b32_e32 v28, v38, v55
	v_mov_b32_e32 v29, v39
	v_or_b32_e32 v38, v38, v54
	v_lshlrev_b64 v[30:31], 12, v[30:31]
	ds_write_b64 v1, v[34:35] offset:37632
	ds_read_b128 v[198:201], v216 offset:36864
	ds_read_b128 v[202:205], v216 offset:36880
	ds_read2_b32 v[206:207], v220 offset1:16
	s_waitcnt lgkmcnt(0)
	v_mul_f32_e32 v210, 0x41800000, v200
	v_mul_f32_e32 v211, 0x41800000, v202
	v_mul_f32_e32 v212, 0x41800000, v204
	v_fma_f32 v213, -v204, v199, v203
	v_fma_f32 v121, -v198, v120, v121
	v_fma_f32 v123, -v198, v122, v123
	ds_write_b128 v218, v[120:123]
	v_fma_f32 v124, -v210, v120, v124
	v_fma_f32 v125, -v211, v120, v125
	v_fma_f32 v125, -v212, v121, v125
	v_fma_f32 v126, -v210, v122, v126
	v_fma_f32 v127, -v211, v122, v127
	v_fma_f32 v127, -v212, v123, v127
	ds_write_b128 v218, v[124:127] offset:256
	v_fma_f32 v129, -v198, v128, v129
	v_fma_f32 v131, -v198, v130, v131
	ds_write_b128 v218, v[128:131] offset:512
	v_fma_f32 v132, -v210, v128, v132
	v_fma_f32 v133, -v211, v128, v133
	v_fma_f32 v133, -v212, v129, v133
	v_fma_f32 v134, -v210, v130, v134
	v_fma_f32 v135, -v211, v130, v135
	v_fma_f32 v135, -v212, v131, v135
	ds_write_b128 v218, v[132:135] offset:768
	v_fma_f32 v182, -v199, v186, v182
	v_fma_f32 v183, -v199, v187, v183
	v_fma_f32 v184, -v199, v188, v184
	v_fma_f32 v185, -v199, v189, v185
	ds_write_b128 v218, v[182:185] offset:1280
	v_mul_f32_e32 v208, v206, v201
	v_mul_f32_e32 v209, v206, v213
	v_fmac_f32_e32 v209, v207, v205
	ds_write_b128 v222, v[206:209]
	v_lshlrev_b64 v[34:35], 1, v[28:29]
	v_lshlrev_b64 v[44:45], 1, v[38:39]
	s_mov_b32 s7, 0x40000
	v_lshl_add_u64 v[52:53], v[32:33], 0, v[30:31]
	v_lshl_add_u64 v[28:29], s[70:71], 0, v[34:35]
	v_lshl_add_u64 v[30:31], s[12:13], 0, v[34:35]
	v_lshl_add_u64 v[32:33], s[14:15], 0, v[34:35]
	v_lshl_add_u64 v[36:37], s[16:17], 0, v[34:35]
	v_lshl_add_u64 v[40:41], s[18:19], 0, v[34:35]
	v_lshl_add_u64 v[38:39], s[70:71], 0, v[44:45]
	v_lshl_add_u64 v[42:43], s[12:13], 0, v[44:45]
	v_lshl_add_u64 v[46:47], s[14:15], 0, v[44:45]
	v_add_co_u32_e32 v48, vcc, s7, v56
	global_load_dwordx2 v[28:29], v[28:29], off
	s_nop 0
	global_load_dwordx2 v[30:31], v[30:31], off
	s_nop 0
	global_load_dwordx2 v[32:33], v[32:33], off
	s_nop 0
	global_load_dwordx2 v[34:35], v[36:37], off
	s_nop 0
	global_load_dwordx2 v[36:37], v[40:41], off
	s_nop 0
	global_load_dwordx2 v[40:41], v[38:39], off
	s_nop 0
	global_load_dwordx2 v[38:39], v[42:43], off
	s_nop 0
	global_load_dwordx2 v[42:43], v[46:47], off
	v_lshl_add_u64 v[46:47], s[16:17], 0, v[44:45]
	v_lshl_add_u64 v[44:45], s[18:19], 0, v[44:45]
	v_addc_co_u32_e32 v49, vcc, 0, v57, vcc
	global_load_dwordx2 v[46:47], v[46:47], off
	s_nop 0
	global_load_dwordx2 v[44:45], v[44:45], off
	v_or_b32_e32 v3, v60, v58
	global_load_dword v81, v[48:49], off
	v_lshlrev_b32_e32 v3, 6, v3
	v_add_u32_e32 v3, 0, v3
	v_bfe_u32 v177, v152, 4, 1
	v_sub_u32_e32 v176, 0, v177
	v_lshlrev_b32_e32 v178, 6, v177
	v_sub_u32_e32 v179, 64, v178
	v_bfe_u32 v177, v152, 1, 2
	v_add_u32_e32 v180, 0, v177
	v_and_b32_e32 v180, 3, v180
	v_lshlrev_b32_e32 v180, 4, v180
	v_add3_u32 v160, v3, v178, v180
	v_add3_u32 v164, v3, v179, v180
	v_add_u32_e32 v180, 1, v177
	v_and_b32_e32 v180, 3, v180
	v_lshlrev_b32_e32 v180, 4, v180
	v_add3_u32 v161, v3, v178, v180
	v_add3_u32 v165, v3, v179, v180
	v_add_u32_e32 v180, 2, v177
	v_and_b32_e32 v180, 3, v180
	v_lshlrev_b32_e32 v180, 4, v180
	v_add3_u32 v162, v3, v178, v180
	v_add3_u32 v166, v3, v179, v180
	v_add_u32_e32 v180, 3, v177
	v_and_b32_e32 v180, 3, v180
	v_lshlrev_b32_e32 v180, 4, v180
	v_add3_u32 v163, v3, v178, v180
	v_add3_u32 v167, v3, v179, v180
	v_add_u32_e32 v168, 0x11b00, v160
	v_add_u32_e32 v169, 0x11b00, v161
	v_add_u32_e32 v170, 0x11b00, v162
	v_add_u32_e32 v171, 0x11b00, v163
	v_add_u32_e32 v172, 0x11b00, v164
	v_add_u32_e32 v173, 0x11b00, v165
	v_add_u32_e32 v174, 0x11b00, v166
	v_add_u32_e32 v175, 0x11b00, v167
	ds_read_b128 v[120:123], v160 offset:39680
	ds_read_b128 v[124:127], v161 offset:39680
	ds_read_b128 v[128:131], v162 offset:39680
	ds_read_b128 v[132:135], v163 offset:39680
	ds_read_b128 v[136:139], v164 offset:39680
	ds_read_b128 v[140:143], v165 offset:39680
	ds_read_b128 v[144:147], v166 offset:39680
	ds_read_b128 v[148:151], v167 offset:39680
	s_movk_i32 s7, 0x7fff
	v_mov_b32_e32 v82, 1
	s_mov_b32 s9, 0xffff0000
	s_lshl_b32 s10, s2, 20
	s_and_b32 s10, s10, 0x4000000
	s_waitcnt lgkmcnt(0)
	v_pk_add_f32 v[120:121], v[120:121], v[124:125]
	v_pk_add_f32 v[122:123], v[122:123], v[126:127]
	v_pk_add_f32 v[128:129], v[128:129], v[132:133]
	v_pk_add_f32 v[130:131], v[130:131], v[134:135]
	v_pk_add_f32 v[120:121], v[120:121], v[128:129]
	v_pk_add_f32 v[122:123], v[122:123], v[130:131]
	v_pk_add_f32 v[120:121], v[120:121], v[122:123]
	v_add_f32_e32 v120, v120, v121
	v_pk_add_f32 v[136:137], v[136:137], v[140:141]
	v_pk_add_f32 v[138:139], v[138:139], v[142:143]
	v_pk_add_f32 v[144:145], v[144:145], v[148:149]
	v_pk_add_f32 v[146:147], v[146:147], v[150:151]
	v_pk_add_f32 v[136:137], v[136:137], v[144:145]
	v_pk_add_f32 v[138:139], v[138:139], v[146:147]
	v_pk_add_f32 v[136:137], v[136:137], v[138:139]
	v_add_f32_e32 v136, v136, v137
	v_bfi_b32 v49, v176, v136, v120
	v_bfi_b32 v48, v176, v120, v136
	v_and_b32_sdwa v50, v49, v82 dst_sel:DWORD dst_unused:UNUSED_PAD src0_sel:WORD_1 src1_sel:DWORD
	v_and_b32_sdwa v51, v48, v82 dst_sel:DWORD dst_unused:UNUSED_PAD src0_sel:WORD_1 src1_sel:DWORD
	v_add3_u32 v49, v49, v50, s7
	v_add3_u32 v48, v48, v51, s7
	v_lshrrev_b32_e32 v49, 16, v49
	v_and_or_b32 v48, v48, s9, v49
	global_store_dword v[52:53], v48, off
	v_lshlrev_b64 v[48:49], 12, v[4:5]
	v_lshl_add_u64 v[48:49], s[10:11], 0, v[48:49]
	s_lshl_b32 s10, s25, 5
	v_and_b32_e32 v50, 7, v153
	s_and_b32 s14, s10, 0x780
	v_lshlrev_b32_e32 v52, 2, v50
	v_lshlrev_b64 v[50:51], 11, v[4:5]
	v_or_b32_e32 v48, s14, v48
	s_and_b32 s15, s24, 0x60
	v_or_b32_e32 v50, s14, v50
	v_or3_b32 v48, v48, s15, v52
	v_or3_b32 v50, v50, s15, v52
	v_lshlrev_b64 v[52:53], 11, v[26:27]
	v_lshl_add_u64 v[48:49], s[78:79], 0, v[48:49]
	s_mov_b64 s[12:13], 0xf040000
	s_lshl_b32 s10, s2, 19
	v_lshl_or_b32 v52, v55, 1, v52
	v_lshl_add_u64 v[48:49], v[48:49], 0, s[12:13]
	s_and_b32 s10, s10, 0x2000000
	v_lshl_add_u64 v[50:51], s[70:71], 0, v[50:51]
	v_lshl_add_u64 v[26:27], s[70:71], 0, v[52:53]
	v_lshl_add_u64 v[52:53], s[78:79], 0, v[52:53]
	s_mov_b32 s12, 0x3d800000
	s_mov_b64 s[14:15], 0x40000
	s_mov_b32 s13, s11
	s_cselect_b32 s62, 1, 0
	s_add_i32 s61, s61, 1
	s_waitcnt lgkmcnt(0)
	v_mov_b32_e32 v226, s61
	s_mov_b64 s[58:59], exec
	s_mov_b64 exec, 1
	ds_write_b32 v224, v226
	s_mov_b64 exec, s[58:59]
	s_sub_i32 s63, s61, 1

.LBB0_667:
	s_or_b64 exec, exec, s[16:17]
	s_waitcnt vmcnt(2)
	v_cvt_f32_f16_sdwa v55, v79 dst_sel:DWORD dst_unused:UNUSED_PAD src0_sel:WORD_1
	v_cvt_f32_f16_e32 v54, v79
	s_add_i32 s13, s13, 2
	s_cmpk_gt_u32 s13, 0x1fc
	v_lshl_add_u64 v[58:59], v[26:27], 0, s[10:11]
	ds_write_b64 v78, v[54:55]
	ds_read_b128 v[198:201], v217 offset:36864
	ds_read_b128 v[202:205], v217 offset:36880
	ds_read2_b32 v[206:207], v221 offset1:16
	s_waitcnt lgkmcnt(0)
	v_mul_f32_e32 v210, 0x41800000, v200
	v_mul_f32_e32 v211, 0x41800000, v202
	v_mul_f32_e32 v212, 0x41800000, v204
	v_fma_f32 v213, -v204, v199, v203
	v_fma_f32 v121, -v198, v120, v121
	v_fma_f32 v123, -v198, v122, v123
	ds_write_b128 v219, v[120:123]
	v_fma_f32 v124, -v210, v120, v124
	v_fma_f32 v125, -v211, v120, v125
	v_fma_f32 v125, -v212, v121, v125
	v_fma_f32 v126, -v210, v122, v126
	v_fma_f32 v127, -v211, v122, v127
	v_fma_f32 v127, -v212, v123, v127
	ds_write_b128 v219, v[124:127] offset:256
	v_fma_f32 v129, -v198, v128, v129
	v_fma_f32 v131, -v198, v130, v131
	ds_write_b128 v219, v[128:131] offset:512
	v_fma_f32 v132, -v210, v128, v132
	v_fma_f32 v133, -v211, v128, v133
	v_fma_f32 v133, -v212, v129, v133
	v_fma_f32 v134, -v210, v130, v134
	v_fma_f32 v135, -v211, v130, v135
	v_fma_f32 v135, -v212, v131, v135
	ds_write_b128 v219, v[132:135] offset:768
	v_fma_f32 v182, -v199, v186, v182
	v_fma_f32 v183, -v199, v187, v183
	v_fma_f32 v184, -v199, v188, v184
	v_fma_f32 v185, -v199, v189, v185
	ds_write_b128 v219, v[182:185] offset:1280
	v_mul_f32_e32 v208, v206, v201
	v_mul_f32_e32 v209, v206, v213
	v_fmac_f32_e32 v209, v207, v205
	ds_write_b128 v223, v[206:209]
	v_lshl_add_u64 v[56:57], v[52:53], 0, s[10:11]
	v_lshl_add_u64 v[54:55], v[50:51], 0, s[10:11]
	s_cbranch_scc1 .LBB0_669
	v_add_co_u32_e32 v10, vcc, 0x50000, v58
	s_nop 1
	v_addc_co_u32_e32 v11, vcc, 0, v59, vcc
	v_add_co_u32_e32 v12, vcc, 0x4050000, v58
	s_nop 1
	v_addc_co_u32_e32 v13, vcc, 0, v59, vcc
	v_add_co_u32_e32 v14, vcc, 0x8050000, v58
	s_nop 1
	v_addc_co_u32_e32 v15, vcc, 0, v59, vcc
	v_add_co_u32_e32 v24, vcc, 0x30050000, v56
	s_nop 1
	v_addc_co_u32_e32 v25, vcc, 0, v57, vcc
	v_add_co_u32_e32 v22, vcc, 0x34050000, v56
	s_nop 1
	v_addc_co_u32_e32 v23, vcc, 0, v57, vcc
	global_load_dwordx2 v[6:7], v[10:11], off
	global_load_dwordx2 v[8:9], v[12:13], off
	global_load_dwordx2 v[16:17], v[12:13], off offset:2048
	global_load_dwordx2 v[18:19], v[10:11], off offset:2048
	s_nop 0
	global_load_dwordx2 v[10:11], v[14:15], off
	global_load_dwordx2 v[20:21], v[14:15], off offset:2048
	global_load_dwordx2 v[12:13], v[24:25], off
	s_nop 0
	global_load_dwordx2 v[14:15], v[22:23], off
	s_nop 0
	global_load_dwordx2 v[22:23], v[22:23], off offset:2048
	s_nop 0
	global_load_dwordx2 v[24:25], v[24:25], off offset:2048
	v_add_co_u32_e32 v60, vcc, 0xc050000, v54
	s_nop 1
	v_addc_co_u32_e32 v61, vcc, 0, v55, vcc
	global_load_dword v79, v[60:61], off

.LBB0_672:
	s_or_b64 exec, exec, s[18:19]
	s_waitcnt vmcnt(2)
	v_cvt_f32_f16_sdwa v61, v81 dst_sel:DWORD dst_unused:UNUSED_PAD src0_sel:WORD_1
	v_cvt_f32_f16_e32 v60, v81
	ds_write_b64 v1, v[60:61] offset:37632
	ds_read_b128 v[198:201], v216 offset:36864
	ds_read_b128 v[202:205], v216 offset:36880
	ds_read2_b32 v[206:207], v220 offset1:16
	s_waitcnt lgkmcnt(0)
	v_mul_f32_e32 v210, 0x41800000, v200
	v_mul_f32_e32 v211, 0x41800000, v202
	v_mul_f32_e32 v212, 0x41800000, v204
	v_fma_f32 v213, -v204, v199, v203
	v_fma_f32 v121, -v198, v120, v121
	v_fma_f32 v123, -v198, v122, v123
	ds_write_b128 v218, v[120:123]
	v_fma_f32 v124, -v210, v120, v124
	v_fma_f32 v125, -v211, v120, v125
	v_fma_f32 v125, -v212, v121, v125
	v_fma_f32 v126, -v210, v122, v126
	v_fma_f32 v127, -v211, v122, v127
	v_fma_f32 v127, -v212, v123, v127
	ds_write_b128 v218, v[124:127] offset:256
	v_fma_f32 v129, -v198, v128, v129
	v_fma_f32 v131, -v198, v130, v131
	ds_write_b128 v218, v[128:131] offset:512
	v_fma_f32 v132, -v210, v128, v132
	v_fma_f32 v133, -v211, v128, v133
	v_fma_f32 v133, -v212, v129, v133
	v_fma_f32 v134, -v210, v130, v134
	v_fma_f32 v135, -v211, v130, v135
	v_fma_f32 v135, -v212, v131, v135
	ds_write_b128 v218, v[132:135] offset:768
	v_fma_f32 v182, -v199, v186, v182
	v_fma_f32 v183, -v199, v187, v183
	v_fma_f32 v184, -v199, v188, v184
	v_fma_f32 v185, -v199, v189, v185
	ds_write_b128 v218, v[182:185] offset:1280
	v_mul_f32_e32 v208, v206, v201
	v_mul_f32_e32 v209, v206, v213
	v_fmac_f32_e32 v209, v207, v205
	ds_write_b128 v222, v[206:209]
